# balanced LDS-DMA staging also in the mixer-out and both o-projection GEMM K-loops
# speedup vs baseline: 1.0106x; 1.0106x over previous
.LBB0_651:
	s_add_u32 s14, s94, 0xf200000
	s_addc_u32 s15, s95, 0
	s_add_u32 s16, s94, 0x12000000
	s_mov_b64 s[18:19], 0x80
	s_addc_u32 s17, s95, 0
	s_bfe_u32 s43, s33, 0x20006
	s_add_i32 m0, s39, 0x18000
	v_lshl_add_u64 v[6:7], v[6:7], 0, s[18:19]
	s_lshl_b32 s44, s3, 6
	s_lshl_b32 s45, s43, 5
	s_waitcnt vmcnt(2)
	s_barrier
	global_load_lds_dwordx4 v[6:7], off
	v_lshl_add_u64 v[4:5], v[4:5], 0, s[18:19]
	s_add_i32 m0, s39, 0x1a000
	s_add_i32 s46, s39, 0x8000
	s_add_i32 s47, s39, 0xa000
	global_load_lds_dwordx4 v[4:5], off
	v_lshl_add_u64 v[0:1], v[0:1], 0, s[18:19]
	s_mov_b32 m0, s46
	s_add_u32 s20, s8, 0x80080
	global_load_lds_dwordx4 v[0:1], off
	v_lshl_add_u64 v[0:1], v[2:3], 0, s[18:19]
	s_mov_b32 m0, s47
	s_addc_u32 s21, s9, 0
	global_load_lds_dwordx4 v[0:1], off
	s_add_i32 m0, s39, 0x1c000
	v_lshl_add_u64 v[0:1], s[20:21], 0, v[188:189]
	global_load_lds_dwordx4 v[0:1], off
	v_lshl_add_u64 v[0:1], s[20:21], 0, v[184:185]
	s_add_i32 m0, s39, 0x1e000
	v_and_b32_e32 v229, 15, v9
	global_load_lds_dwordx4 v[0:1], off
	v_and_b32_e32 v0, 48, v9
	v_and_b32_e32 v1, 0xfffffc00, v11
	v_lshlrev_b32_e32 v3, 2, v9
	s_cmpk_lt_u32 s33, 0x100
	v_lshl_add_u32 v2, s3, 13, v1
	v_lshl_or_b32 v0, v229, 6, v0
	v_and_b32_e32 v3, 32, v3
	v_lshl_add_u32 v1, s43, 12, v1
	s_cselect_b64 s[22:23], -1, 0
	s_lshl_b32 s0, s0, 20
	v_bitop3_b32 v2, v0, v2, v3 bitop3:0xde
	v_bitop3_b32 v3, v0, v1, v3 bitop3:0xde
	s_lshl_b32 s1, s1, 24
	v_lshlrev_b32_e32 v0, 15, v13
	s_or_b32 s0, s2, s0
	v_and_b32_e32 v0, 0xffff0000, v0
	s_add_u32 s0, s94, s0
	v_lshl_add_u32 v0, v14, 12, v0
	v_and_b32_e32 v1, 1, v13
	s_addc_u32 s2, s95, 0
	v_lshl_or_b32 v0, v1, 6, v0
	s_add_u32 s0, s0, s1
	v_lshl_add_u32 v0, v15, 1, v0
	v_mov_b32_e32 v1, v189
	s_addc_u32 s1, s2, 0
	v_lshl_add_u64 v[192:193], s[0:1], 0, v[0:1]
	v_lshlrev_b32_e32 v0, 15, v8
	v_and_b32_e32 v0, 0xffff0000, v0
	v_lshl_add_u32 v0, v10, 12, v0
	v_and_b32_e32 v1, 1, v8
	v_lshl_or_b32 v0, v1, 6, v0
	s_waitcnt vmcnt(6)
	v_lshl_add_u32 v0, v12, 1, v0
	v_mov_b32_e32 v1, v189
	s_add_i32 s50, 0, 0x10000
	s_add_i32 s52, 0, 0x14000
	v_lshl_add_u64 v[194:195], s[0:1], 0, v[0:1]
	v_add_u32_e32 v230, s50, v3
	v_add_u32_e32 v231, s52, v3
	v_mbcnt_lo_u32_b32 v0, -1, 0
	s_add_i32 s50, s50, s37
	s_add_i32 s52, s52, s37
	s_add_i32 s55, 0, 0x18000
	s_add_i32 s54, 0, 0x1c000
	v_ashrrev_i32_e32 v228, 4, v9
	s_mov_b32 s21, 0
	v_add_u32_e32 v232, 0, v2
	s_mov_b64 s[24:25], 0x1387ff80
	s_lshr_b32 s84, s88, 2
	s_mul_i32 s85, s84, 0x3000
	s_add_i32 s85, s85, s39
	s_mul_i32 s96, s84, 0x60000
	s_mov_b32 s97, 0
	s_sub_u32 s86, s24, 0x80000
	s_subb_u32 s87, s25, 0
	s_add_u32 s86, s86, s96
	s_addc_u32 s87, s87, 0
	v_mbcnt_hi_u32_b32 v233, -1, v0
	s_add_i32 s48, s39, 0xc000
	s_add_i32 s49, s39, 0xe000
	s_add_i32 s51, s50, 0x2000
	s_add_i32 s53, s52, 0x2000
	v_add_u32_e32 v234, s55, v3
	v_add_u32_e32 v235, s54, v3
	s_add_i32 s55, s55, s37
	s_mov_b32 s56, 0
	s_barrier
	s_branch .LBB0_654

.LBB0_655:
	ds_read_b128 v[120:123], v230
	ds_read_b128 v[132:135], v230 offset:1024
	ds_read_b128 v[136:139], v230 offset:2048
	ds_read_b128 v[140:143], v230 offset:3072
	ds_read_b128 v[144:147], v231
	ds_read_b128 v[148:151], v231 offset:1024
	ds_read_b128 v[152:155], v231 offset:2048
	ds_read_b128 v[156:159], v231 offset:3072
	s_add_u32 s28, s0, s2
	s_addc_u32 s29, s1, s3
	s_cmpk_eq_i32 s2, 0x1000
	s_cselect_b32 s30, 0, s2
	s_cselect_b32 s31, 0, s3
	s_cselect_b32 s28, s57, s28
	s_cselect_b32 s29, s7, s29
	s_add_u32 s30, s10, s30
	s_addc_u32 s31, s11, s31
	s_add_u32 s98, s2, s86
	s_addc_u32 s99, s3, s87
	s_add_i32 m0, s85, 0x8000
	v_lshl_add_u64 v[204:205], v[192:193], 0, s[98:99]
	ds_read_b128 v[160:163], v232
	ds_read_b128 v[164:167], v232 offset:1024
	ds_read_b128 v[168:171], v232 offset:2048
	ds_read_b128 v[172:175], v232 offset:3072
	ds_read_b128 v[176:179], v232 offset:4096
	ds_read_b128 v[180:183], v232 offset:5120
	ds_read_b128 v[196:199], v232 offset:6144
	ds_read_b128 v[200:203], v232 offset:7168
	global_load_lds_dwordx4 v[204:205], off
	s_add_u32 s98, s98, 0x20000
	s_addc_u32 s99, s99, 0
	s_add_i32 m0, s85, 0x9000
	v_lshl_add_u64 v[204:205], v[192:193], 0, s[98:99]
	global_load_lds_dwordx4 v[204:205], off
	s_add_u32 s98, s98, 0x20000
	s_addc_u32 s99, s99, 0
	s_add_i32 m0, s85, 0xa000
	v_lshl_add_u64 v[204:205], v[192:193], 0, s[98:99]
	global_load_lds_dwordx4 v[204:205], off
	s_add_u32 s98, s98, 0x20000
	s_addc_u32 s99, s99, 0
	s_add_i32 m0, s85, 0xb000
	v_lshl_add_u64 v[204:205], v[192:193], 0, s[98:99]
	global_load_lds_dwordx4 v[204:205], off
	s_waitcnt vmcnt(8)
	s_waitcnt lgkmcnt(0)
	s_barrier
	s_setprio 1
	s_waitcnt lgkmcnt(0)
	v_mfma_f32_16x16x32_bf16 v[128:131], v[120:123], v[160:163], v[128:131]
	v_mfma_f32_16x16x32_bf16 v[124:127], v[136:139], v[160:163], v[124:127]
	v_mfma_f32_16x16x32_bf16 v[108:111], v[120:123], v[168:171], v[108:111]
	v_mfma_f32_16x16x32_bf16 v[104:107], v[136:139], v[168:171], v[104:107]
	v_mfma_f32_16x16x32_bf16 v[92:95], v[120:123], v[176:179], v[92:95]
	v_mfma_f32_16x16x32_bf16 v[88:91], v[136:139], v[176:179], v[88:91]
	v_mfma_f32_16x16x32_bf16 v[76:79], v[120:123], v[196:199], v[76:79]
	v_mfma_f32_16x16x32_bf16 v[72:75], v[136:139], v[196:199], v[72:75]
	v_mfma_f32_16x16x32_bf16 v[128:131], v[132:135], v[164:167], v[128:131]
	v_mfma_f32_16x16x32_bf16 v[124:127], v[140:143], v[164:167], v[124:127]
	v_mfma_f32_16x16x32_bf16 v[108:111], v[132:135], v[172:175], v[108:111]
	v_mfma_f32_16x16x32_bf16 v[104:107], v[140:143], v[172:175], v[104:107]
	v_mfma_f32_16x16x32_bf16 v[92:95], v[132:135], v[180:183], v[92:95]
	v_mfma_f32_16x16x32_bf16 v[88:91], v[140:143], v[180:183], v[88:91]
	v_mfma_f32_16x16x32_bf16 v[76:79], v[132:135], v[200:203], v[76:79]
	v_mfma_f32_16x16x32_bf16 v[72:75], v[140:143], v[200:203], v[72:75]
	s_setprio 0
	s_setprio 1
	v_mfma_f32_16x16x32_bf16 v[116:119], v[144:147], v[160:163], v[116:119]
	v_mfma_f32_16x16x32_bf16 v[112:115], v[152:155], v[160:163], v[112:115]
	v_mfma_f32_16x16x32_bf16 v[100:103], v[144:147], v[168:171], v[100:103]
	v_mfma_f32_16x16x32_bf16 v[96:99], v[152:155], v[168:171], v[96:99]
	v_mfma_f32_16x16x32_bf16 v[84:87], v[144:147], v[176:179], v[84:87]
	v_mfma_f32_16x16x32_bf16 v[80:83], v[152:155], v[176:179], v[80:83]
	v_mfma_f32_16x16x32_bf16 v[68:71], v[144:147], v[196:199], v[68:71]
	v_mfma_f32_16x16x32_bf16 v[64:67], v[152:155], v[196:199], v[64:67]
	v_mfma_f32_16x16x32_bf16 v[116:119], v[148:151], v[164:167], v[116:119]
	v_mfma_f32_16x16x32_bf16 v[112:115], v[156:159], v[164:167], v[112:115]
	v_mfma_f32_16x16x32_bf16 v[100:103], v[148:151], v[172:175], v[100:103]
	v_mfma_f32_16x16x32_bf16 v[96:99], v[156:159], v[172:175], v[96:99]
	v_mfma_f32_16x16x32_bf16 v[84:87], v[148:151], v[180:183], v[84:87]
	v_mfma_f32_16x16x32_bf16 v[80:83], v[156:159], v[180:183], v[80:83]
	v_mfma_f32_16x16x32_bf16 v[68:71], v[148:151], v[200:203], v[68:71]
	v_mfma_f32_16x16x32_bf16 v[64:67], v[156:159], v[200:203], v[64:67]
	s_setprio 0
	s_barrier
	s_mov_b32 m0, s50
	v_lshl_add_u64 v[204:205], s[28:29], 0, v[188:189]
	s_add_u32 s60, s28, 0x80000
	ds_read_b128 v[160:163], v232 offset:16384
	ds_read_b128 v[164:167], v232 offset:17408
	ds_read_b128 v[168:171], v232 offset:18432
	ds_read_b128 v[172:175], v232 offset:19456
	ds_read_b128 v[176:179], v232 offset:20480
	ds_read_b128 v[180:183], v232 offset:21504
	ds_read_b128 v[196:199], v232 offset:22528
	ds_read_b128 v[200:203], v232 offset:23552
	global_load_lds_dwordx4 v[204:205], off
	v_lshl_add_u64 v[206:207], s[28:29], 0, v[184:185]
	s_mov_b32 m0, s51
	s_addc_u32 s61, s29, 0
	global_load_lds_dwordx4 v[206:207], off
	v_lshl_add_u64 v[208:209], s[60:61], 0, v[188:189]
	s_mov_b32 m0, s52
	global_load_lds_dwordx4 v[208:209], off
	v_lshl_add_u64 v[208:209], s[60:61], 0, v[184:185]
	s_mov_b32 m0, s53
	s_nop 0
	global_load_lds_dwordx4 v[208:209], off
	s_waitcnt vmcnt(8)
	s_waitcnt lgkmcnt(0)
	s_barrier
	s_setprio 1
	s_waitcnt lgkmcnt(0)
	v_mfma_f32_16x16x32_bf16 v[60:63], v[120:123], v[160:163], v[60:63]
	v_mfma_f32_16x16x32_bf16 v[56:59], v[136:139], v[160:163], v[56:59]
	v_mfma_f32_16x16x32_bf16 v[44:47], v[120:123], v[168:171], v[44:47]
	v_mfma_f32_16x16x32_bf16 v[40:43], v[136:139], v[168:171], v[40:43]
	v_mfma_f32_16x16x32_bf16 v[28:31], v[120:123], v[176:179], v[28:31]
	v_mfma_f32_16x16x32_bf16 v[24:27], v[136:139], v[176:179], v[24:27]
	v_mfma_f32_16x16x32_bf16 v[12:15], v[120:123], v[196:199], v[12:15]
	v_mfma_f32_16x16x32_bf16 v[8:11], v[136:139], v[196:199], v[8:11]
	v_mfma_f32_16x16x32_bf16 v[60:63], v[132:135], v[164:167], v[60:63]
	v_mfma_f32_16x16x32_bf16 v[56:59], v[140:143], v[164:167], v[56:59]
	v_mfma_f32_16x16x32_bf16 v[44:47], v[132:135], v[172:175], v[44:47]
	v_mfma_f32_16x16x32_bf16 v[40:43], v[140:143], v[172:175], v[40:43]
	v_mfma_f32_16x16x32_bf16 v[28:31], v[132:135], v[180:183], v[28:31]
	v_mfma_f32_16x16x32_bf16 v[24:27], v[140:143], v[180:183], v[24:27]
	v_mfma_f32_16x16x32_bf16 v[12:15], v[132:135], v[200:203], v[12:15]
	v_mfma_f32_16x16x32_bf16 v[8:11], v[140:143], v[200:203], v[8:11]
	s_setprio 0
	s_setprio 1
	v_mfma_f32_16x16x32_bf16 v[52:55], v[144:147], v[160:163], v[52:55]
	v_mfma_f32_16x16x32_bf16 v[48:51], v[152:155], v[160:163], v[48:51]
	v_mfma_f32_16x16x32_bf16 v[36:39], v[144:147], v[168:171], v[36:39]
	v_mfma_f32_16x16x32_bf16 v[32:35], v[152:155], v[168:171], v[32:35]
	v_mfma_f32_16x16x32_bf16 v[20:23], v[144:147], v[176:179], v[20:23]
	v_mfma_f32_16x16x32_bf16 v[16:19], v[152:155], v[176:179], v[16:19]
	v_mfma_f32_16x16x32_bf16 v[4:7], v[144:147], v[196:199], v[4:7]
	v_mfma_f32_16x16x32_bf16 v[0:3], v[152:155], v[196:199], v[0:3]
	v_mfma_f32_16x16x32_bf16 v[52:55], v[148:151], v[164:167], v[52:55]
	v_mfma_f32_16x16x32_bf16 v[48:51], v[156:159], v[164:167], v[48:51]
	v_mfma_f32_16x16x32_bf16 v[36:39], v[148:151], v[172:175], v[36:39]
	v_mfma_f32_16x16x32_bf16 v[32:35], v[156:159], v[172:175], v[32:35]
	v_mfma_f32_16x16x32_bf16 v[20:23], v[148:151], v[180:183], v[20:23]
	v_mfma_f32_16x16x32_bf16 v[16:19], v[156:159], v[180:183], v[16:19]
	v_mfma_f32_16x16x32_bf16 v[4:7], v[148:151], v[200:203], v[4:7]
	v_mfma_f32_16x16x32_bf16 v[0:3], v[156:159], v[200:203], v[0:3]
	s_setprio 0
	s_waitcnt vmcnt(4)
	s_barrier
	ds_read_b128 v[120:123], v234
	ds_read_b128 v[132:135], v234 offset:1024
	ds_read_b128 v[136:139], v234 offset:2048
	ds_read_b128 v[140:143], v234 offset:3072
	ds_read_b128 v[144:147], v235
	ds_read_b128 v[148:151], v235 offset:1024
	ds_read_b128 v[152:155], v235 offset:2048
	ds_read_b128 v[156:159], v235 offset:3072
	s_add_u32 s98, s30, s96
	s_addc_u32 s99, s31, s97
	s_add_i32 m0, s85, 0
	v_lshl_add_u64 v[212:213], s[98:99], 0, v[190:191]
	ds_read_b128 v[160:163], v232 offset:32768
	ds_read_b128 v[164:167], v232 offset:33792
	ds_read_b128 v[168:171], v232 offset:34816
	ds_read_b128 v[172:175], v232 offset:35840
	ds_read_b128 v[176:179], v232 offset:36864
	ds_read_b128 v[180:183], v232 offset:37888
	ds_read_b128 v[196:199], v232 offset:38912
	ds_read_b128 v[200:203], v232 offset:39936
	global_load_lds_dwordx4 v[212:213], off
	s_add_u32 s98, s98, 0x20000
	s_addc_u32 s99, s99, 0
	s_add_i32 m0, s85, 0x1000
	v_lshl_add_u64 v[212:213], s[98:99], 0, v[190:191]
	global_load_lds_dwordx4 v[212:213], off
	s_add_u32 s98, s98, 0x20000
	s_addc_u32 s99, s99, 0
	s_add_i32 m0, s85, 0x2000
	v_lshl_add_u64 v[212:213], s[98:99], 0, v[190:191]
	global_load_lds_dwordx4 v[212:213], off
	s_add_u32 s98, s98, 0x20000
	s_addc_u32 s99, s99, 0
	s_add_i32 m0, s85, 0x3000
	v_lshl_add_u64 v[212:213], s[98:99], 0, v[190:191]
	global_load_lds_dwordx4 v[212:213], off
	s_waitcnt vmcnt(8)
	s_waitcnt lgkmcnt(0)
	s_barrier
	s_setprio 1
	s_waitcnt lgkmcnt(0)
	v_mfma_f32_16x16x32_bf16 v[128:131], v[120:123], v[160:163], v[128:131]
	v_mfma_f32_16x16x32_bf16 v[124:127], v[136:139], v[160:163], v[124:127]
	v_mfma_f32_16x16x32_bf16 v[108:111], v[120:123], v[168:171], v[108:111]
	v_mfma_f32_16x16x32_bf16 v[104:107], v[136:139], v[168:171], v[104:107]
	v_mfma_f32_16x16x32_bf16 v[92:95], v[120:123], v[176:179], v[92:95]
	v_mfma_f32_16x16x32_bf16 v[88:91], v[136:139], v[176:179], v[88:91]
	v_mfma_f32_16x16x32_bf16 v[76:79], v[120:123], v[196:199], v[76:79]
	v_mfma_f32_16x16x32_bf16 v[72:75], v[136:139], v[196:199], v[72:75]
	v_mfma_f32_16x16x32_bf16 v[128:131], v[132:135], v[164:167], v[128:131]
	v_mfma_f32_16x16x32_bf16 v[124:127], v[140:143], v[164:167], v[124:127]
	v_mfma_f32_16x16x32_bf16 v[108:111], v[132:135], v[172:175], v[108:111]
	v_mfma_f32_16x16x32_bf16 v[104:107], v[140:143], v[172:175], v[104:107]
	v_mfma_f32_16x16x32_bf16 v[92:95], v[132:135], v[180:183], v[92:95]
	v_mfma_f32_16x16x32_bf16 v[88:91], v[140:143], v[180:183], v[88:91]
	v_mfma_f32_16x16x32_bf16 v[76:79], v[132:135], v[200:203], v[76:79]
	v_mfma_f32_16x16x32_bf16 v[72:75], v[140:143], v[200:203], v[72:75]
	s_setprio 0
	s_setprio 1
	v_mfma_f32_16x16x32_bf16 v[116:119], v[144:147], v[160:163], v[116:119]
	v_mfma_f32_16x16x32_bf16 v[112:115], v[152:155], v[160:163], v[112:115]
	v_mfma_f32_16x16x32_bf16 v[100:103], v[144:147], v[168:171], v[100:103]
	v_mfma_f32_16x16x32_bf16 v[96:99], v[152:155], v[168:171], v[96:99]
	v_mfma_f32_16x16x32_bf16 v[84:87], v[144:147], v[176:179], v[84:87]
	v_mfma_f32_16x16x32_bf16 v[80:83], v[152:155], v[176:179], v[80:83]
	v_mfma_f32_16x16x32_bf16 v[68:71], v[144:147], v[196:199], v[68:71]
	v_mfma_f32_16x16x32_bf16 v[64:67], v[152:155], v[196:199], v[64:67]
	v_mfma_f32_16x16x32_bf16 v[116:119], v[148:151], v[164:167], v[116:119]
	v_mfma_f32_16x16x32_bf16 v[112:115], v[156:159], v[164:167], v[112:115]
	v_mfma_f32_16x16x32_bf16 v[100:103], v[148:151], v[172:175], v[100:103]
	v_mfma_f32_16x16x32_bf16 v[96:99], v[156:159], v[172:175], v[96:99]
	v_mfma_f32_16x16x32_bf16 v[84:87], v[148:151], v[180:183], v[84:87]
	v_mfma_f32_16x16x32_bf16 v[80:83], v[156:159], v[180:183], v[80:83]
	v_mfma_f32_16x16x32_bf16 v[68:71], v[148:151], v[200:203], v[68:71]
	v_mfma_f32_16x16x32_bf16 v[64:67], v[156:159], v[200:203], v[64:67]
	s_setprio 0
	s_barrier
	s_mov_b32 m0, s55
	v_lshl_add_u64 v[204:205], v[204:205], 0, s[18:19]
	ds_read_b128 v[160:163], v232 offset:49152
	ds_read_b128 v[164:167], v232 offset:50176
	ds_read_b128 v[168:171], v232 offset:51200
	ds_read_b128 v[172:175], v232 offset:52224
	ds_read_b128 v[176:179], v232 offset:53248
	ds_read_b128 v[180:183], v232 offset:54272
	ds_read_b128 v[196:199], v232 offset:55296
	ds_read_b128 v[200:203], v232 offset:56320
	global_load_lds_dwordx4 v[204:205], off
	s_add_i32 m0, s55, 0x2000
	s_add_u32 s28, s28, 0x80080
	v_lshl_add_u64 v[204:205], v[206:207], 0, s[18:19]
	s_addc_u32 s29, s29, 0
	s_add_i32 s30, s54, s37
	global_load_lds_dwordx4 v[204:205], off
	v_lshl_add_u64 v[204:205], s[28:29], 0, v[188:189]
	s_mov_b32 m0, s30
	s_nop 0
	global_load_lds_dwordx4 v[204:205], off
	v_lshl_add_u64 v[204:205], s[28:29], 0, v[184:185]
	s_add_i32 m0, s30, 0x2000
	s_nop 0
	global_load_lds_dwordx4 v[204:205], off
	s_waitcnt vmcnt(8)
	s_waitcnt lgkmcnt(0)
	s_barrier
	s_setprio 1
	s_waitcnt lgkmcnt(0)
	v_mfma_f32_16x16x32_bf16 v[60:63], v[120:123], v[160:163], v[60:63]
	v_mfma_f32_16x16x32_bf16 v[56:59], v[136:139], v[160:163], v[56:59]
	v_mfma_f32_16x16x32_bf16 v[44:47], v[120:123], v[168:171], v[44:47]
	v_mfma_f32_16x16x32_bf16 v[40:43], v[136:139], v[168:171], v[40:43]
	v_mfma_f32_16x16x32_bf16 v[28:31], v[120:123], v[176:179], v[28:31]
	v_mfma_f32_16x16x32_bf16 v[24:27], v[136:139], v[176:179], v[24:27]
	v_mfma_f32_16x16x32_bf16 v[12:15], v[120:123], v[196:199], v[12:15]
	v_mfma_f32_16x16x32_bf16 v[8:11], v[136:139], v[196:199], v[8:11]
	v_mfma_f32_16x16x32_bf16 v[60:63], v[132:135], v[164:167], v[60:63]
	v_mfma_f32_16x16x32_bf16 v[56:59], v[140:143], v[164:167], v[56:59]
	v_mfma_f32_16x16x32_bf16 v[44:47], v[132:135], v[172:175], v[44:47]
	v_mfma_f32_16x16x32_bf16 v[40:43], v[140:143], v[172:175], v[40:43]
	v_mfma_f32_16x16x32_bf16 v[28:31], v[132:135], v[180:183], v[28:31]
	v_mfma_f32_16x16x32_bf16 v[24:27], v[140:143], v[180:183], v[24:27]
	v_mfma_f32_16x16x32_bf16 v[12:15], v[132:135], v[200:203], v[12:15]
	v_mfma_f32_16x16x32_bf16 v[8:11], v[140:143], v[200:203], v[8:11]
	s_setprio 0
	s_setprio 1
	v_mfma_f32_16x16x32_bf16 v[52:55], v[144:147], v[160:163], v[52:55]
	v_mfma_f32_16x16x32_bf16 v[48:51], v[152:155], v[160:163], v[48:51]
	v_mfma_f32_16x16x32_bf16 v[36:39], v[144:147], v[168:171], v[36:39]
	v_mfma_f32_16x16x32_bf16 v[32:35], v[152:155], v[168:171], v[32:35]
	v_mfma_f32_16x16x32_bf16 v[20:23], v[144:147], v[176:179], v[20:23]
	v_mfma_f32_16x16x32_bf16 v[16:19], v[152:155], v[176:179], v[16:19]
	v_mfma_f32_16x16x32_bf16 v[4:7], v[144:147], v[196:199], v[4:7]
	v_mfma_f32_16x16x32_bf16 v[0:3], v[152:155], v[196:199], v[0:3]
	v_mfma_f32_16x16x32_bf16 v[52:55], v[148:151], v[164:167], v[52:55]
	v_mfma_f32_16x16x32_bf16 v[48:51], v[156:159], v[164:167], v[48:51]
	v_mfma_f32_16x16x32_bf16 v[36:39], v[148:151], v[172:175], v[36:39]
	v_mfma_f32_16x16x32_bf16 v[32:35], v[156:159], v[172:175], v[32:35]
	v_mfma_f32_16x16x32_bf16 v[20:23], v[148:151], v[180:183], v[20:23]
	v_mfma_f32_16x16x32_bf16 v[16:19], v[156:159], v[180:183], v[16:19]
	v_mfma_f32_16x16x32_bf16 v[4:7], v[148:151], v[200:203], v[4:7]
	v_mfma_f32_16x16x32_bf16 v[0:3], v[156:159], v[200:203], v[0:3]
	s_setprio 0
	s_waitcnt vmcnt(4)
	s_barrier
	s_add_i32 s58, s58, 2
	s_add_u32 s2, s2, 0x100
	s_addc_u32 s3, s3, 0
	s_cmp_gt_u32 s58, 29
	s_cbranch_scc0 .LBB0_655
	s_and_b64 vcc, exec, s[22:23]
	s_cbranch_vccz .LBB0_658
	s_barrier

.LBB0_950:
	s_add_u32 s14, s94, 0xf200000
	s_addc_u32 s15, s95, 0
	s_add_u32 s16, s94, 0x12000000
	s_mov_b64 s[18:19], 0x80
	s_addc_u32 s17, s95, 0
	s_bfe_u32 s43, s33, 0x20006
	s_add_i32 m0, s39, 0x18000
	v_lshl_add_u64 v[6:7], v[6:7], 0, s[18:19]
	s_lshl_b32 s44, s3, 6
	s_lshl_b32 s45, s43, 5
	s_waitcnt vmcnt(2)
	s_barrier
	global_load_lds_dwordx4 v[6:7], off
	v_lshl_add_u64 v[4:5], v[4:5], 0, s[18:19]
	s_add_i32 m0, s39, 0x1a000
	s_add_i32 s46, s39, 0x8000
	s_add_i32 s47, s39, 0xa000
	global_load_lds_dwordx4 v[4:5], off
	v_lshl_add_u64 v[0:1], v[0:1], 0, s[18:19]
	s_mov_b32 m0, s46
	s_add_u32 s20, s8, 0x80080
	global_load_lds_dwordx4 v[0:1], off
	v_lshl_add_u64 v[0:1], v[2:3], 0, s[18:19]
	s_mov_b32 m0, s47
	s_addc_u32 s21, s9, 0
	global_load_lds_dwordx4 v[0:1], off
	s_add_i32 m0, s39, 0x1c000
	v_lshl_add_u64 v[0:1], s[20:21], 0, v[188:189]
	global_load_lds_dwordx4 v[0:1], off
	v_lshl_add_u64 v[0:1], s[20:21], 0, v[184:185]
	s_add_i32 m0, s39, 0x1e000
	v_and_b32_e32 v229, 15, v9
	global_load_lds_dwordx4 v[0:1], off
	v_and_b32_e32 v0, 48, v9
	v_and_b32_e32 v1, 0xfffffc00, v11
	v_lshlrev_b32_e32 v3, 2, v9
	s_cmpk_lt_u32 s33, 0x100
	v_lshl_add_u32 v2, s3, 13, v1
	v_lshl_or_b32 v0, v229, 6, v0
	v_and_b32_e32 v3, 32, v3
	v_lshl_add_u32 v1, s43, 12, v1
	s_cselect_b64 s[22:23], -1, 0
	s_lshl_b32 s0, s0, 20
	v_bitop3_b32 v2, v0, v2, v3 bitop3:0xde
	v_bitop3_b32 v3, v0, v1, v3 bitop3:0xde
	s_lshl_b32 s1, s1, 24
	v_lshlrev_b32_e32 v0, 15, v13
	s_or_b32 s0, s2, s0
	v_and_b32_e32 v0, 0xffff0000, v0
	s_add_u32 s0, s94, s0
	v_lshl_add_u32 v0, v14, 12, v0
	v_and_b32_e32 v1, 1, v13
	s_addc_u32 s2, s95, 0
	v_lshl_or_b32 v0, v1, 6, v0
	s_add_u32 s0, s0, s1
	v_lshl_add_u32 v0, v15, 1, v0
	v_mov_b32_e32 v1, v189
	s_addc_u32 s1, s2, 0
	v_lshl_add_u64 v[192:193], s[0:1], 0, v[0:1]
	v_lshlrev_b32_e32 v0, 15, v8
	v_and_b32_e32 v0, 0xffff0000, v0
	v_lshl_add_u32 v0, v10, 12, v0
	v_and_b32_e32 v1, 1, v8
	v_lshl_or_b32 v0, v1, 6, v0
	s_waitcnt vmcnt(6)
	v_lshl_add_u32 v0, v12, 1, v0
	v_mov_b32_e32 v1, v189
	s_add_i32 s50, 0, 0x10000
	s_add_i32 s52, 0, 0x14000
	v_lshl_add_u64 v[194:195], s[0:1], 0, v[0:1]
	v_add_u32_e32 v230, s50, v3
	v_add_u32_e32 v231, s52, v3
	v_mbcnt_lo_u32_b32 v0, -1, 0
	s_add_i32 s50, s50, s37
	s_add_i32 s52, s52, s37
	s_add_i32 s55, 0, 0x18000
	s_add_i32 s54, 0, 0x1c000
	v_ashrrev_i32_e32 v228, 4, v9
	s_mov_b32 s21, 0
	v_add_u32_e32 v232, 0, v2
	s_mov_b64 s[24:25], 0x1407ff80
	s_lshr_b32 s84, s88, 2
	s_mul_i32 s85, s84, 0x3000
	s_add_i32 s85, s85, s39
	s_mul_i32 s96, s84, 0x60000
	s_mov_b32 s97, 0
	s_sub_u32 s86, s24, 0x80000
	s_subb_u32 s87, s25, 0
	s_add_u32 s86, s86, s96
	s_addc_u32 s87, s87, 0
	v_mbcnt_hi_u32_b32 v233, -1, v0
	s_add_i32 s48, s39, 0xc000
	s_add_i32 s49, s39, 0xe000
	s_add_i32 s51, s50, 0x2000
	s_add_i32 s53, s52, 0x2000
	v_add_u32_e32 v234, s55, v3
	v_add_u32_e32 v235, s54, v3
	s_add_i32 s55, s55, s37
	s_mov_b32 s56, 0
	s_barrier
	s_branch .LBB0_953

.LBB0_1825:
	ds_read_b128 v[120:123], v230
	ds_read_b128 v[132:135], v230 offset:1024
	ds_read_b128 v[136:139], v230 offset:2048
	ds_read_b128 v[140:143], v230 offset:3072
	ds_read_b128 v[144:147], v231
	ds_read_b128 v[148:151], v231 offset:1024
	ds_read_b128 v[152:155], v231 offset:2048
	ds_read_b128 v[156:159], v231 offset:3072
	s_add_u32 s28, s0, s2
	s_addc_u32 s29, s1, s3
	s_cmpk_eq_i32 s2, 0x1000
	s_cselect_b32 s30, 0, s2
	s_cselect_b32 s31, 0, s3
	s_cselect_b32 s28, s57, s28
	s_cselect_b32 s29, s5, s29
	s_add_u32 s30, s10, s30
	s_addc_u32 s31, s11, s31
	s_add_u32 s98, s2, s86
	s_addc_u32 s99, s3, s87
	s_add_i32 m0, s85, 0x8000
	v_lshl_add_u64 v[204:205], v[192:193], 0, s[98:99]
	ds_read_b128 v[160:163], v232
	ds_read_b128 v[164:167], v232 offset:1024
	ds_read_b128 v[168:171], v232 offset:2048
	ds_read_b128 v[172:175], v232 offset:3072
	ds_read_b128 v[176:179], v232 offset:4096
	ds_read_b128 v[180:183], v232 offset:5120
	ds_read_b128 v[196:199], v232 offset:6144
	ds_read_b128 v[200:203], v232 offset:7168
	global_load_lds_dwordx4 v[204:205], off
	s_add_u32 s98, s98, 0x20000
	s_addc_u32 s99, s99, 0
	s_add_i32 m0, s85, 0x9000
	v_lshl_add_u64 v[204:205], v[192:193], 0, s[98:99]
	global_load_lds_dwordx4 v[204:205], off
	s_add_u32 s98, s98, 0x20000
	s_addc_u32 s99, s99, 0
	s_add_i32 m0, s85, 0xa000
	v_lshl_add_u64 v[204:205], v[192:193], 0, s[98:99]
	global_load_lds_dwordx4 v[204:205], off
	s_add_u32 s98, s98, 0x20000
	s_addc_u32 s99, s99, 0
	s_add_i32 m0, s85, 0xb000
	v_lshl_add_u64 v[204:205], v[192:193], 0, s[98:99]
	global_load_lds_dwordx4 v[204:205], off
	s_waitcnt vmcnt(8)
	s_waitcnt lgkmcnt(0)
	s_barrier
	s_setprio 1
	s_waitcnt lgkmcnt(0)
	v_mfma_f32_16x16x32_bf16 v[128:131], v[120:123], v[160:163], v[128:131]
	v_mfma_f32_16x16x32_bf16 v[124:127], v[136:139], v[160:163], v[124:127]
	v_mfma_f32_16x16x32_bf16 v[108:111], v[120:123], v[168:171], v[108:111]
	v_mfma_f32_16x16x32_bf16 v[104:107], v[136:139], v[168:171], v[104:107]
	v_mfma_f32_16x16x32_bf16 v[92:95], v[120:123], v[176:179], v[92:95]
	v_mfma_f32_16x16x32_bf16 v[88:91], v[136:139], v[176:179], v[88:91]
	v_mfma_f32_16x16x32_bf16 v[76:79], v[120:123], v[196:199], v[76:79]
	v_mfma_f32_16x16x32_bf16 v[72:75], v[136:139], v[196:199], v[72:75]
	v_mfma_f32_16x16x32_bf16 v[128:131], v[132:135], v[164:167], v[128:131]
	v_mfma_f32_16x16x32_bf16 v[124:127], v[140:143], v[164:167], v[124:127]
	v_mfma_f32_16x16x32_bf16 v[108:111], v[132:135], v[172:175], v[108:111]
	v_mfma_f32_16x16x32_bf16 v[104:107], v[140:143], v[172:175], v[104:107]
	v_mfma_f32_16x16x32_bf16 v[92:95], v[132:135], v[180:183], v[92:95]
	v_mfma_f32_16x16x32_bf16 v[88:91], v[140:143], v[180:183], v[88:91]
	v_mfma_f32_16x16x32_bf16 v[76:79], v[132:135], v[200:203], v[76:79]
	v_mfma_f32_16x16x32_bf16 v[72:75], v[140:143], v[200:203], v[72:75]
	s_setprio 0
	s_setprio 1
	v_mfma_f32_16x16x32_bf16 v[116:119], v[144:147], v[160:163], v[116:119]
	v_mfma_f32_16x16x32_bf16 v[112:115], v[152:155], v[160:163], v[112:115]
	v_mfma_f32_16x16x32_bf16 v[100:103], v[144:147], v[168:171], v[100:103]
	v_mfma_f32_16x16x32_bf16 v[96:99], v[152:155], v[168:171], v[96:99]
	v_mfma_f32_16x16x32_bf16 v[84:87], v[144:147], v[176:179], v[84:87]
	v_mfma_f32_16x16x32_bf16 v[80:83], v[152:155], v[176:179], v[80:83]
	v_mfma_f32_16x16x32_bf16 v[68:71], v[144:147], v[196:199], v[68:71]
	v_mfma_f32_16x16x32_bf16 v[64:67], v[152:155], v[196:199], v[64:67]
	v_mfma_f32_16x16x32_bf16 v[116:119], v[148:151], v[164:167], v[116:119]
	v_mfma_f32_16x16x32_bf16 v[112:115], v[156:159], v[164:167], v[112:115]
	v_mfma_f32_16x16x32_bf16 v[100:103], v[148:151], v[172:175], v[100:103]
	v_mfma_f32_16x16x32_bf16 v[96:99], v[156:159], v[172:175], v[96:99]
	v_mfma_f32_16x16x32_bf16 v[84:87], v[148:151], v[180:183], v[84:87]
	v_mfma_f32_16x16x32_bf16 v[80:83], v[156:159], v[180:183], v[80:83]
	v_mfma_f32_16x16x32_bf16 v[68:71], v[148:151], v[200:203], v[68:71]
	v_mfma_f32_16x16x32_bf16 v[64:67], v[156:159], v[200:203], v[64:67]
	s_setprio 0
	s_barrier
	s_mov_b32 m0, s50
	v_lshl_add_u64 v[204:205], s[28:29], 0, v[188:189]
	s_add_u32 s60, s28, 0x80000
	ds_read_b128 v[160:163], v232 offset:16384
	ds_read_b128 v[164:167], v232 offset:17408
	ds_read_b128 v[168:171], v232 offset:18432
	ds_read_b128 v[172:175], v232 offset:19456
	ds_read_b128 v[176:179], v232 offset:20480
	ds_read_b128 v[180:183], v232 offset:21504
	ds_read_b128 v[196:199], v232 offset:22528
	ds_read_b128 v[200:203], v232 offset:23552
	global_load_lds_dwordx4 v[204:205], off
	v_lshl_add_u64 v[206:207], s[28:29], 0, v[184:185]
	s_mov_b32 m0, s51
	s_addc_u32 s61, s29, 0
	global_load_lds_dwordx4 v[206:207], off
	v_lshl_add_u64 v[208:209], s[60:61], 0, v[188:189]
	s_mov_b32 m0, s52
	global_load_lds_dwordx4 v[208:209], off
	v_lshl_add_u64 v[208:209], s[60:61], 0, v[184:185]
	s_mov_b32 m0, s53
	s_nop 0
	global_load_lds_dwordx4 v[208:209], off
	s_waitcnt vmcnt(8)
	s_waitcnt lgkmcnt(0)
	s_barrier
	s_setprio 1
	s_waitcnt lgkmcnt(0)
	v_mfma_f32_16x16x32_bf16 v[60:63], v[120:123], v[160:163], v[60:63]
	v_mfma_f32_16x16x32_bf16 v[56:59], v[136:139], v[160:163], v[56:59]
	v_mfma_f32_16x16x32_bf16 v[44:47], v[120:123], v[168:171], v[44:47]
	v_mfma_f32_16x16x32_bf16 v[40:43], v[136:139], v[168:171], v[40:43]
	v_mfma_f32_16x16x32_bf16 v[28:31], v[120:123], v[176:179], v[28:31]
	v_mfma_f32_16x16x32_bf16 v[24:27], v[136:139], v[176:179], v[24:27]
	v_mfma_f32_16x16x32_bf16 v[12:15], v[120:123], v[196:199], v[12:15]
	v_mfma_f32_16x16x32_bf16 v[8:11], v[136:139], v[196:199], v[8:11]
	v_mfma_f32_16x16x32_bf16 v[60:63], v[132:135], v[164:167], v[60:63]
	v_mfma_f32_16x16x32_bf16 v[56:59], v[140:143], v[164:167], v[56:59]
	v_mfma_f32_16x16x32_bf16 v[44:47], v[132:135], v[172:175], v[44:47]
	v_mfma_f32_16x16x32_bf16 v[40:43], v[140:143], v[172:175], v[40:43]
	v_mfma_f32_16x16x32_bf16 v[28:31], v[132:135], v[180:183], v[28:31]
	v_mfma_f32_16x16x32_bf16 v[24:27], v[140:143], v[180:183], v[24:27]
	v_mfma_f32_16x16x32_bf16 v[12:15], v[132:135], v[200:203], v[12:15]
	v_mfma_f32_16x16x32_bf16 v[8:11], v[140:143], v[200:203], v[8:11]
	s_setprio 0
	s_setprio 1
	v_mfma_f32_16x16x32_bf16 v[52:55], v[144:147], v[160:163], v[52:55]
	v_mfma_f32_16x16x32_bf16 v[48:51], v[152:155], v[160:163], v[48:51]
	v_mfma_f32_16x16x32_bf16 v[36:39], v[144:147], v[168:171], v[36:39]
	v_mfma_f32_16x16x32_bf16 v[32:35], v[152:155], v[168:171], v[32:35]
	v_mfma_f32_16x16x32_bf16 v[20:23], v[144:147], v[176:179], v[20:23]
	v_mfma_f32_16x16x32_bf16 v[16:19], v[152:155], v[176:179], v[16:19]
	v_mfma_f32_16x16x32_bf16 v[4:7], v[144:147], v[196:199], v[4:7]
	v_mfma_f32_16x16x32_bf16 v[0:3], v[152:155], v[196:199], v[0:3]
	v_mfma_f32_16x16x32_bf16 v[52:55], v[148:151], v[164:167], v[52:55]
	v_mfma_f32_16x16x32_bf16 v[48:51], v[156:159], v[164:167], v[48:51]
	v_mfma_f32_16x16x32_bf16 v[36:39], v[148:151], v[172:175], v[36:39]
	v_mfma_f32_16x16x32_bf16 v[32:35], v[156:159], v[172:175], v[32:35]
	v_mfma_f32_16x16x32_bf16 v[20:23], v[148:151], v[180:183], v[20:23]
	v_mfma_f32_16x16x32_bf16 v[16:19], v[156:159], v[180:183], v[16:19]
	v_mfma_f32_16x16x32_bf16 v[4:7], v[148:151], v[200:203], v[4:7]
	v_mfma_f32_16x16x32_bf16 v[0:3], v[156:159], v[200:203], v[0:3]
	s_setprio 0
	s_waitcnt vmcnt(4)
	s_barrier
	ds_read_b128 v[120:123], v234
	ds_read_b128 v[132:135], v234 offset:1024
	ds_read_b128 v[136:139], v234 offset:2048
	ds_read_b128 v[140:143], v234 offset:3072
	ds_read_b128 v[144:147], v235
	ds_read_b128 v[148:151], v235 offset:1024
	ds_read_b128 v[152:155], v235 offset:2048
	ds_read_b128 v[156:159], v235 offset:3072
	s_add_u32 s98, s30, s96
	s_addc_u32 s99, s31, s97
	s_add_i32 m0, s85, 0
	v_lshl_add_u64 v[212:213], s[98:99], 0, v[190:191]
	ds_read_b128 v[160:163], v232 offset:32768
	ds_read_b128 v[164:167], v232 offset:33792
	ds_read_b128 v[168:171], v232 offset:34816
	ds_read_b128 v[172:175], v232 offset:35840
	ds_read_b128 v[176:179], v232 offset:36864
	ds_read_b128 v[180:183], v232 offset:37888
	ds_read_b128 v[196:199], v232 offset:38912
	ds_read_b128 v[200:203], v232 offset:39936
	global_load_lds_dwordx4 v[212:213], off
	s_add_u32 s98, s98, 0x20000
	s_addc_u32 s99, s99, 0
	s_add_i32 m0, s85, 0x1000
	v_lshl_add_u64 v[212:213], s[98:99], 0, v[190:191]
	global_load_lds_dwordx4 v[212:213], off
	s_add_u32 s98, s98, 0x20000
	s_addc_u32 s99, s99, 0
	s_add_i32 m0, s85, 0x2000
	v_lshl_add_u64 v[212:213], s[98:99], 0, v[190:191]
	global_load_lds_dwordx4 v[212:213], off
	s_add_u32 s98, s98, 0x20000
	s_addc_u32 s99, s99, 0
	s_add_i32 m0, s85, 0x3000
	v_lshl_add_u64 v[212:213], s[98:99], 0, v[190:191]
	global_load_lds_dwordx4 v[212:213], off
	s_waitcnt vmcnt(8)
	s_waitcnt lgkmcnt(0)
	s_barrier
	s_setprio 1
	s_waitcnt lgkmcnt(0)
	v_mfma_f32_16x16x32_bf16 v[128:131], v[120:123], v[160:163], v[128:131]
	v_mfma_f32_16x16x32_bf16 v[124:127], v[136:139], v[160:163], v[124:127]
	v_mfma_f32_16x16x32_bf16 v[108:111], v[120:123], v[168:171], v[108:111]
	v_mfma_f32_16x16x32_bf16 v[104:107], v[136:139], v[168:171], v[104:107]
	v_mfma_f32_16x16x32_bf16 v[92:95], v[120:123], v[176:179], v[92:95]
	v_mfma_f32_16x16x32_bf16 v[88:91], v[136:139], v[176:179], v[88:91]
	v_mfma_f32_16x16x32_bf16 v[76:79], v[120:123], v[196:199], v[76:79]
	v_mfma_f32_16x16x32_bf16 v[72:75], v[136:139], v[196:199], v[72:75]
	v_mfma_f32_16x16x32_bf16 v[128:131], v[132:135], v[164:167], v[128:131]
	v_mfma_f32_16x16x32_bf16 v[124:127], v[140:143], v[164:167], v[124:127]
	v_mfma_f32_16x16x32_bf16 v[108:111], v[132:135], v[172:175], v[108:111]
	v_mfma_f32_16x16x32_bf16 v[104:107], v[140:143], v[172:175], v[104:107]
	v_mfma_f32_16x16x32_bf16 v[92:95], v[132:135], v[180:183], v[92:95]
	v_mfma_f32_16x16x32_bf16 v[88:91], v[140:143], v[180:183], v[88:91]
	v_mfma_f32_16x16x32_bf16 v[76:79], v[132:135], v[200:203], v[76:79]
	v_mfma_f32_16x16x32_bf16 v[72:75], v[140:143], v[200:203], v[72:75]
	s_setprio 0
	s_setprio 1
	v_mfma_f32_16x16x32_bf16 v[116:119], v[144:147], v[160:163], v[116:119]
	v_mfma_f32_16x16x32_bf16 v[112:115], v[152:155], v[160:163], v[112:115]
	v_mfma_f32_16x16x32_bf16 v[100:103], v[144:147], v[168:171], v[100:103]
	v_mfma_f32_16x16x32_bf16 v[96:99], v[152:155], v[168:171], v[96:99]
	v_mfma_f32_16x16x32_bf16 v[84:87], v[144:147], v[176:179], v[84:87]
	v_mfma_f32_16x16x32_bf16 v[80:83], v[152:155], v[176:179], v[80:83]
	v_mfma_f32_16x16x32_bf16 v[68:71], v[144:147], v[196:199], v[68:71]
	v_mfma_f32_16x16x32_bf16 v[64:67], v[152:155], v[196:199], v[64:67]
	v_mfma_f32_16x16x32_bf16 v[116:119], v[148:151], v[164:167], v[116:119]
	v_mfma_f32_16x16x32_bf16 v[112:115], v[156:159], v[164:167], v[112:115]
	v_mfma_f32_16x16x32_bf16 v[100:103], v[148:151], v[172:175], v[100:103]
	v_mfma_f32_16x16x32_bf16 v[96:99], v[156:159], v[172:175], v[96:99]
	v_mfma_f32_16x16x32_bf16 v[84:87], v[148:151], v[180:183], v[84:87]
	v_mfma_f32_16x16x32_bf16 v[80:83], v[156:159], v[180:183], v[80:83]
	v_mfma_f32_16x16x32_bf16 v[68:71], v[148:151], v[200:203], v[68:71]
	v_mfma_f32_16x16x32_bf16 v[64:67], v[156:159], v[200:203], v[64:67]
	s_setprio 0
	s_barrier
	s_mov_b32 m0, s55
	v_lshl_add_u64 v[204:205], v[204:205], 0, s[18:19]
	ds_read_b128 v[160:163], v232 offset:49152
	ds_read_b128 v[164:167], v232 offset:50176
	ds_read_b128 v[168:171], v232 offset:51200
	ds_read_b128 v[172:175], v232 offset:52224
	ds_read_b128 v[176:179], v232 offset:53248
	ds_read_b128 v[180:183], v232 offset:54272
	ds_read_b128 v[196:199], v232 offset:55296
	ds_read_b128 v[200:203], v232 offset:56320
	global_load_lds_dwordx4 v[204:205], off
	s_add_i32 m0, s55, 0x2000
	s_add_u32 s28, s28, 0x80080
	v_lshl_add_u64 v[204:205], v[206:207], 0, s[18:19]
	s_addc_u32 s29, s29, 0
	s_add_i32 s30, s54, s37
	global_load_lds_dwordx4 v[204:205], off
	v_lshl_add_u64 v[204:205], s[28:29], 0, v[188:189]
	s_mov_b32 m0, s30
	s_nop 0
	global_load_lds_dwordx4 v[204:205], off
	v_lshl_add_u64 v[204:205], s[28:29], 0, v[184:185]
	s_add_i32 m0, s30, 0x2000
	s_nop 0
	global_load_lds_dwordx4 v[204:205], off
	s_waitcnt vmcnt(8)
	s_waitcnt lgkmcnt(0)
	s_barrier
	s_setprio 1
	s_waitcnt lgkmcnt(0)
	v_mfma_f32_16x16x32_bf16 v[60:63], v[120:123], v[160:163], v[60:63]
	v_mfma_f32_16x16x32_bf16 v[56:59], v[136:139], v[160:163], v[56:59]
	v_mfma_f32_16x16x32_bf16 v[44:47], v[120:123], v[168:171], v[44:47]
	v_mfma_f32_16x16x32_bf16 v[40:43], v[136:139], v[168:171], v[40:43]
	v_mfma_f32_16x16x32_bf16 v[28:31], v[120:123], v[176:179], v[28:31]
	v_mfma_f32_16x16x32_bf16 v[24:27], v[136:139], v[176:179], v[24:27]
	v_mfma_f32_16x16x32_bf16 v[12:15], v[120:123], v[196:199], v[12:15]
	v_mfma_f32_16x16x32_bf16 v[8:11], v[136:139], v[196:199], v[8:11]
	v_mfma_f32_16x16x32_bf16 v[60:63], v[132:135], v[164:167], v[60:63]
	v_mfma_f32_16x16x32_bf16 v[56:59], v[140:143], v[164:167], v[56:59]
	v_mfma_f32_16x16x32_bf16 v[44:47], v[132:135], v[172:175], v[44:47]
	v_mfma_f32_16x16x32_bf16 v[40:43], v[140:143], v[172:175], v[40:43]
	v_mfma_f32_16x16x32_bf16 v[28:31], v[132:135], v[180:183], v[28:31]
	v_mfma_f32_16x16x32_bf16 v[24:27], v[140:143], v[180:183], v[24:27]
	v_mfma_f32_16x16x32_bf16 v[12:15], v[132:135], v[200:203], v[12:15]
	v_mfma_f32_16x16x32_bf16 v[8:11], v[140:143], v[200:203], v[8:11]
	s_setprio 0
	s_setprio 1
	v_mfma_f32_16x16x32_bf16 v[52:55], v[144:147], v[160:163], v[52:55]
	v_mfma_f32_16x16x32_bf16 v[48:51], v[152:155], v[160:163], v[48:51]
	v_mfma_f32_16x16x32_bf16 v[36:39], v[144:147], v[168:171], v[36:39]
	v_mfma_f32_16x16x32_bf16 v[32:35], v[152:155], v[168:171], v[32:35]
	v_mfma_f32_16x16x32_bf16 v[20:23], v[144:147], v[176:179], v[20:23]
	v_mfma_f32_16x16x32_bf16 v[16:19], v[152:155], v[176:179], v[16:19]
	v_mfma_f32_16x16x32_bf16 v[4:7], v[144:147], v[196:199], v[4:7]
	v_mfma_f32_16x16x32_bf16 v[0:3], v[152:155], v[196:199], v[0:3]
	v_mfma_f32_16x16x32_bf16 v[52:55], v[148:151], v[164:167], v[52:55]
	v_mfma_f32_16x16x32_bf16 v[48:51], v[156:159], v[164:167], v[48:51]
	v_mfma_f32_16x16x32_bf16 v[36:39], v[148:151], v[172:175], v[36:39]
	v_mfma_f32_16x16x32_bf16 v[32:35], v[156:159], v[172:175], v[32:35]
	v_mfma_f32_16x16x32_bf16 v[20:23], v[148:151], v[180:183], v[20:23]
	v_mfma_f32_16x16x32_bf16 v[16:19], v[156:159], v[180:183], v[16:19]
	v_mfma_f32_16x16x32_bf16 v[4:7], v[148:151], v[200:203], v[4:7]
	v_mfma_f32_16x16x32_bf16 v[0:3], v[156:159], v[200:203], v[0:3]
	s_setprio 0
	s_waitcnt vmcnt(4)
	s_barrier
	s_add_i32 s58, s58, 2
	s_add_u32 s2, s2, 0x100
	s_addc_u32 s3, s3, 0
	s_cmp_gt_u32 s58, 29
	s_cbranch_scc0 .LBB0_1825
	s_and_b64 vcc, exec, s[22:23]
	s_cbranch_vccz .LBB0_1828
	s_barrier
